# attention KV loop: packed f32 multiplies/adds of the O rescale split into scalar f32 ops
# baseline (speedup 1.0000x reference)
.LBB0_563:
	s_add_i32 s16, s13, -1
	ds_read_b128 v[64:67], v187 offset:57344
	ds_read_b128 v[68:71], v202 offset:57344
	ds_read_b128 v[220:223], v189 offset:57344
	ds_read_b128 v[232:235], v201 offset:57344
	v_add_f32_e32 v178, 0, v136
	v_add_f32_e32 v178, v230, v178
	s_waitcnt lgkmcnt(3)
	v_mfma_f32_32x32x16_bf16 v[80:95], v[64:67], v[96:99], 0
	v_add_f32_e32 v178, v137, v178
	v_add_f32_e32 v178, v229, v178
	v_add_f32_e32 v178, v138, v178
	v_add_f32_e32 v178, v228, v178
	v_add_f32_e32 v178, v139, v178
	v_add_f32_e32 v178, v213, v178
	v_add_f32_e32 v178, v144, v178
	s_waitcnt lgkmcnt(2)
	v_mfma_f32_32x32x16_bf16 v[64:79], v[68:71], v[96:99], 0
	v_add_f32_e32 v178, v147, v178
	v_add_f32_e32 v178, v145, v178
	v_add_f32_e32 v178, v146, v178
	v_exp_f32_e32 v132, v132
	v_add_f32_e32 v178, v141, v178
	v_exp_f32_e32 v133, v133
	v_add_f32_e32 v178, v143, v178
	s_waitcnt lgkmcnt(1)
	v_mfma_f32_32x32x16_bf16 v[80:95], v[220:223], v[100:103], v[80:95]
	v_exp_f32_e32 v134, v134
	v_add_f32_e32 v178, v140, v178
	v_exp_f32_e32 v135, v135
	v_add_f32_e32 v178, v142, v178
	v_exp_f32_e32 v124, v124
	v_add_f32_e32 v178, v132, v178
	v_exp_f32_e32 v125, v125
	s_waitcnt lgkmcnt(0)
	v_mfma_f32_32x32x16_bf16 v[64:79], v[232:235], v[100:103], v[64:79]
	ds_read_b128 v[220:223], v190 offset:57344
	ds_read_b128 v[232:235], v209 offset:57344
	v_add_f32_e32 v178, v133, v178
	v_exp_f32_e32 v126, v126
	v_add_f32_e32 v178, v134, v178
	v_exp_f32_e32 v127, v127
	v_add_f32_e32 v178, v135, v178
	v_exp_f32_e32 v128, v128
	s_waitcnt lgkmcnt(1)
	v_mfma_f32_32x32x16_bf16 v[80:95], v[220:223], v[104:107], v[80:95]
	v_add_f32_e32 v178, v124, v178
	v_exp_f32_e32 v129, v129
	v_add_f32_e32 v178, v125, v178
	v_exp_f32_e32 v130, v130
	v_add_f32_e32 v178, v126, v178
	v_exp_f32_e32 v131, v131
	v_add_f32_e32 v178, v127, v178
	s_waitcnt lgkmcnt(0)
	v_mfma_f32_32x32x16_bf16 v[64:79], v[232:235], v[104:107], v[64:79]
	ds_read_b128 v[220:223], v191 offset:57344
	ds_read_b128 v[232:235], v212 offset:57344
	v_exp_f32_e32 v120, v120
	v_add_f32_e32 v178, v128, v178
	v_exp_f32_e32 v121, v121
	v_add_f32_e32 v178, v129, v178
	v_exp_f32_e32 v122, v122
	v_add_f32_e32 v178, v130, v178
	s_waitcnt lgkmcnt(1)
	v_mfma_f32_32x32x16_bf16 v[80:95], v[220:223], v[108:111], v[80:95]
	v_exp_f32_e32 v123, v123
	v_add_f32_e32 v178, v131, v178
	v_add_f32_e32 v178, v120, v178
	v_add_f32_e32 v178, v121, v178
	v_add_f32_e32 v178, v122, v178
	v_add_f32_e32 v231, v123, v178
	s_waitcnt lgkmcnt(0)
	v_mfma_f32_32x32x16_bf16 v[64:79], v[232:235], v[108:111], v[64:79]
	ds_read_b128 v[220:223], v192 offset:57344
	ds_read_b128 v[232:235], v211 offset:57344
	s_waitcnt lgkmcnt(1)
	v_mfma_f32_32x32x16_bf16 v[80:95], v[220:223], v[112:115], v[80:95]
	s_waitcnt lgkmcnt(0)
	v_mfma_f32_32x32x16_bf16 v[64:79], v[232:235], v[112:115], v[64:79]
	ds_read_b128 v[220:223], v193 offset:57344
	ds_read_b128 v[232:235], v210 offset:57344
	s_waitcnt lgkmcnt(1)
	v_mfma_f32_32x32x16_bf16 v[80:95], v[220:223], v[116:119], v[80:95]
	s_waitcnt lgkmcnt(0)
	v_mfma_f32_32x32x16_bf16 v[64:79], v[232:235], v[116:119], v[64:79]
	ds_read_b128 v[220:223], v194 offset:57344
	ds_read_b128 v[232:235], v208 offset:57344
	ds_read_b128 v[236:239], v171
	s_waitcnt lgkmcnt(0)
	v_mfma_f32_32x32x16_bf16 v[80:95], v[220:223], v[236:239], v[80:95]
	v_mfma_f32_32x32x16_bf16 v[64:79], v[232:235], v[236:239], v[64:79]
	ds_read_b128 v[220:223], v195 offset:57344
	ds_read_b128 v[232:235], v207 offset:57344
	ds_read_b128 v[236:239], v171 offset:1024
	s_waitcnt lgkmcnt(0)
	v_mfma_f32_32x32x16_bf16 v[80:95], v[220:223], v[236:239], v[80:95]
	v_mfma_f32_32x32x16_bf16 v[64:79], v[232:235], v[236:239], v[64:79]
	ds_read_b128 v[220:223], v196 offset:57344
	ds_read_b128 v[232:235], v206 offset:57344
	ds_read_b128 v[236:239], v171 offset:2048
	s_waitcnt lgkmcnt(0)
	v_mfma_f32_32x32x16_bf16 v[80:95], v[220:223], v[236:239], v[80:95]
	v_mfma_f32_32x32x16_bf16 v[64:79], v[232:235], v[236:239], v[64:79]
	ds_read_b128 v[220:223], v197 offset:57344
	ds_read_b128 v[232:235], v205 offset:57344
	ds_read_b128 v[236:239], v171 offset:3072
	s_waitcnt lgkmcnt(0)
	v_mfma_f32_32x32x16_bf16 v[80:95], v[220:223], v[236:239], v[80:95]
	v_mfma_f32_32x32x16_bf16 v[64:79], v[232:235], v[236:239], v[64:79]
	ds_read_b128 v[220:223], v199 offset:57344
	ds_read_b128 v[232:235], v204 offset:57344
	ds_read_b128 v[236:239], v171 offset:4096
	s_waitcnt lgkmcnt(0)
	v_mfma_f32_32x32x16_bf16 v[80:95], v[220:223], v[236:239], v[80:95]
	v_mfma_f32_32x32x16_bf16 v[64:79], v[232:235], v[236:239], v[64:79]
	ds_read_b128 v[220:223], v198 offset:57344
	ds_read_b128 v[232:235], v203 offset:57344
	ds_read_b128 v[236:239], v171 offset:5120
	v_cvt_pk_bf16_f32 v136, v136, v230
	v_cvt_pk_bf16_f32 v137, v137, v229
	v_cvt_pk_bf16_f32 v138, v138, v228
	v_cvt_pk_bf16_f32 v139, v139, v213
	v_cvt_pk_bf16_f32 v144, v144, v147
	v_cvt_pk_bf16_f32 v145, v145, v146
	s_waitcnt lgkmcnt(0)
	v_mfma_f32_32x32x16_bf16 v[80:95], v[220:223], v[236:239], v[80:95]
	v_cvt_pk_bf16_f32 v146, v141, v143
	v_cvt_pk_bf16_f32 v147, v140, v142
	v_cvt_pk_bf16_f32 v220, v132, v133
	v_cvt_pk_bf16_f32 v221, v134, v135
	v_cvt_pk_bf16_f32 v222, v124, v125
	v_cvt_pk_bf16_f32 v223, v126, v127
	v_permlane32_swap_b32_e32 v136, v138
	v_mfma_f32_32x32x16_bf16 v[64:79], v[232:235], v[236:239], v[64:79]
	v_mov_b32_e32 v233, v231
	v_cvt_pk_bf16_f32 v234, v128, v129
	v_cvt_pk_bf16_f32 v235, v130, v131
	v_cvt_pk_bf16_f32 v236, v120, v121
	s_nop 1
	v_permlane32_swap_b32_e32 v231, v233
	v_cvt_pk_bf16_f32 v237, v122, v123
	v_permlane32_swap_b32_e32 v234, v236
	v_permlane32_swap_b32_e32 v137, v139
	v_permlane32_swap_b32_e32 v144, v146
	v_permlane32_swap_b32_e32 v145, v147
	v_permlane32_swap_b32_e32 v220, v222
	v_permlane32_swap_b32_e32 v221, v223
	v_permlane32_swap_b32_e32 v235, v237
	s_sub_i32 s4, s14, 64
	s_cmp_lt_u32 s16, 3
	s_cselect_b32 s4, s15, s4
	s_ashr_i32 s5, s4, 31
	s_lshl_b64 s[76:77], s[4:5], 11
	s_mul_hi_i32 s79, s4, s87
	s_mul_i32 s78, s4, s87
	v_lshl_add_u64 v[120:121], v[148:149], 0, s[76:77]
	v_lshl_add_u64 v[124:125], v[156:157], 0, s[76:77]
	v_lshl_add_u64 v[130:131], v[150:151], 0, s[78:79]
	v_lshl_add_u64 v[134:135], v[152:153], 0, s[78:79]
	v_lshl_add_u64 v[140:141], v[154:155], 0, s[78:79]
	global_load_dwordx4 v[120:123], v[120:121], off
	s_nop 0
	global_load_dwordx4 v[124:127], v[124:125], off
	s_nop 0
	global_load_dwordx4 v[128:131], v[130:131], off
	s_nop 0
	global_load_dwordx4 v[132:135], v[134:135], off
	s_nop 0
	global_load_dwordx4 v[140:143], v[140:141], off
	ds_read_b64_tr_b16 v[238:239], v172 offset:0
	ds_read_b64_tr_b16 v[240:241], v172 offset:0x800
	ds_read_b64_tr_b16 v[242:243], v172 offset:0x1000
	ds_read_b64_tr_b16 v[244:245], v172 offset:0x1800
	ds_read_b64_tr_b16 v[246:247], v172 offset:0x2000
	ds_read_b64_tr_b16 v[248:249], v172 offset:0x2800
	ds_read_b64_tr_b16 v[250:251], v172 offset:0x3000
	ds_read_b64_tr_b16 v[252:253], v172 offset:0x3800
	s_waitcnt lgkmcnt(0)
	s_nop 0
	v_mfma_f32_32x32x16_bf16 v[0:15], v[136:139], v[238:241], v[0:15]
	ds_read_b64_tr_b16 v[238:239], v172 offset:0x200
	ds_read_b64_tr_b16 v[240:241], v172 offset:0xa00
	v_mfma_f32_32x32x16_bf16 v[0:15], v[144:147], v[242:245], v[0:15]
	ds_read_b64_tr_b16 v[242:243], v172 offset:0x1200
	ds_read_b64_tr_b16 v[244:245], v172 offset:0x1a00
	v_mfma_f32_32x32x16_bf16 v[0:15], v[220:223], v[246:249], v[0:15]
	ds_read_b64_tr_b16 v[246:247], v172 offset:0x2200
	ds_read_b64_tr_b16 v[248:249], v172 offset:0x2a00
	v_mfma_f32_32x32x16_bf16 v[0:15], v[234:237], v[250:253], v[0:15]
	ds_read_b64_tr_b16 v[250:251], v172 offset:0x3200
	ds_read_b64_tr_b16 v[252:253], v172 offset:0x3a00
	s_waitcnt lgkmcnt(0)
	v_mfma_f32_32x32x16_bf16 v[32:47], v[136:139], v[238:241], v[32:47]
	ds_read_b64_tr_b16 v[238:239], v172 offset:0x400
	ds_read_b64_tr_b16 v[240:241], v172 offset:0xc00
	v_mfma_f32_32x32x16_bf16 v[32:47], v[144:147], v[242:245], v[32:47]
	ds_read_b64_tr_b16 v[242:243], v172 offset:0x1400
	ds_read_b64_tr_b16 v[244:245], v172 offset:0x1c00
	v_mfma_f32_32x32x16_bf16 v[32:47], v[220:223], v[246:249], v[32:47]
	ds_read_b64_tr_b16 v[246:247], v172 offset:0x2400
	ds_read_b64_tr_b16 v[248:249], v172 offset:0x2c00
	v_mfma_f32_32x32x16_bf16 v[32:47], v[234:237], v[250:253], v[32:47]
	ds_read_b64_tr_b16 v[250:251], v172 offset:0x3400
	ds_read_b64_tr_b16 v[252:253], v172 offset:0x3c00
	s_waitcnt lgkmcnt(0)
	v_mfma_f32_32x32x16_bf16 v[16:31], v[136:139], v[238:241], v[16:31]
	ds_read_b64_tr_b16 v[238:239], v172 offset:0x600
	ds_read_b64_tr_b16 v[240:241], v172 offset:0xe00
	v_mfma_f32_32x32x16_bf16 v[16:31], v[144:147], v[242:245], v[16:31]
	ds_read_b64_tr_b16 v[242:243], v172 offset:0x1600
	ds_read_b64_tr_b16 v[244:245], v172 offset:0x1e00
	v_mfma_f32_32x32x16_bf16 v[16:31], v[220:223], v[246:249], v[16:31]
	ds_read_b64_tr_b16 v[246:247], v172 offset:0x2600
	ds_read_b64_tr_b16 v[248:249], v172 offset:0x2e00
	v_mfma_f32_32x32x16_bf16 v[16:31], v[234:237], v[250:253], v[16:31]
	ds_read_b64_tr_b16 v[250:251], v172 offset:0x3600
	ds_read_b64_tr_b16 v[252:253], v172 offset:0x3e00
	s_waitcnt lgkmcnt(0)
	v_mfma_f32_32x32x16_bf16 v[48:63], v[136:139], v[238:241], v[48:63]
	v_max_f32_e32 v136, v81, v81
	v_max_f32_e32 v137, v80, v80
	v_max_f32_e32 v136, v137, v136
	v_max3_f32 v136, v136, v82, v83
	v_max3_f32 v136, v136, v84, v85
	v_max3_f32 v136, v136, v86, v87
	v_max3_f32 v136, v136, v88, v89
	v_max3_f32 v136, v136, v90, v91
	v_mfma_f32_32x32x16_bf16 v[48:63], v[144:147], v[242:245], v[48:63]
	v_max3_f32 v136, v136, v92, v93
	v_max3_f32 v136, v136, v94, v95
	v_max3_f32 v136, v136, v64, v65
	v_max3_f32 v136, v136, v66, v67
	v_max3_f32 v136, v136, v68, v69
	v_max3_f32 v136, v136, v70, v71
	v_max3_f32 v136, v136, v72, v73
	v_max3_f32 v136, v136, v74, v75
	v_mfma_f32_32x32x16_bf16 v[48:63], v[220:223], v[246:249], v[48:63]
	v_max3_f32 v136, v136, v76, v77
	v_max3_f32 v136, v136, v78, v79
	v_mov_b32_e32 v137, v136
	s_nop 1
	v_permlane32_swap_b32_e32 v136, v137
	v_max_f32_e32 v137, v137, v137
	v_max_f32_e32 v136, v136, v136
	v_max_f32_e32 v136, v136, v137
	v_sub_f32_e32 v137, v136, v158
	v_cmp_ge_f32_e32 vcc, s90, v137
	v_max_f32_e32 v137, v158, v158
	v_mfma_f32_32x32x16_bf16 v[48:63], v[234:237], v[250:253], v[48:63]
	v_max_f32_e32 v136, v137, v136
	v_sub_f32_e32 v137, v158, v136
	v_exp_f32_e32 v137, v137
	s_cmp_eq_u64 vcc, exec
	s_cselect_b64 s[4:5], -1, 0
	s_barrier
	s_waitcnt vmcnt(0)
	v_cndmask_b32_e64 v234, v137, 1.0, s[4:5]
	v_cmp_gt_f32_e32 vcc, 1.0, v234
	s_waitcnt vmcnt(4)
	ds_write_b128 v182, v[120:123]
	s_waitcnt vmcnt(3)
	ds_write_b128 v183, v[124:127]
	s_waitcnt vmcnt(2)
	ds_write_b128 v184, v[128:131] offset:32768
	s_waitcnt vmcnt(1)
	ds_write_b128 v185, v[132:135] offset:32768
	s_waitcnt vmcnt(0)
	ds_write_b128 v186, v[140:143] offset:32768
	s_cbranch_vccz .LBB0_567
	s_and_saveexec_b64 s[6:7], s[2:3]
	ds_write_b32 v173, v234 offset:128
	s_or_b64 exec, exec, s[6:7]
	s_waitcnt lgkmcnt(0)
	v_add_u32_e32 v132, v169, v176
	ds_read_b128 v[120:123], v132 offset:224
	ds_read_b128 v[124:127], v132 offset:192
	ds_read_b128 v[128:131], v132 offset:160
	ds_read_b128 v[132:135], v132 offset:128
	s_waitcnt lgkmcnt(3)
	v_mul_f32_e32 v12, v12, v120
	v_mul_f32_e32 v13, v13, v121
	s_waitcnt lgkmcnt(2)
	v_mul_f32_e32 v8, v8, v124
	v_mul_f32_e32 v9, v9, v125
	s_waitcnt lgkmcnt(1)
	v_mul_f32_e32 v4, v4, v128
	v_mul_f32_e32 v5, v5, v129
	v_mul_f32_e32 v14, v14, v122
	v_mul_f32_e32 v15, v15, v123
	v_mul_f32_e32 v10, v10, v126
	v_mul_f32_e32 v11, v11, v127
	v_mul_f32_e32 v6, v6, v130
	v_mul_f32_e32 v7, v7, v131
	s_waitcnt lgkmcnt(0)
	v_mul_f32_e32 v2, v2, v134
	v_mul_f32_e32 v3, v3, v135
	v_mul_f32_e32 v0, v0, v132
	v_mul_f32_e32 v1, v1, v133
	v_mul_f32_e32 v44, v44, v120
	v_mul_f32_e32 v45, v45, v121
	v_mul_f32_e32 v40, v40, v124
	v_mul_f32_e32 v41, v41, v125
	v_mul_f32_e32 v36, v36, v128
	v_mul_f32_e32 v37, v37, v129
	v_mul_f32_e32 v46, v46, v122
	v_mul_f32_e32 v47, v47, v123
	v_mul_f32_e32 v42, v42, v126
	v_mul_f32_e32 v43, v43, v127
	v_mul_f32_e32 v38, v38, v130
	v_mul_f32_e32 v39, v39, v131
	v_mul_f32_e32 v34, v34, v134
	v_mul_f32_e32 v35, v35, v135
	v_mul_f32_e32 v32, v32, v132
	v_mul_f32_e32 v33, v33, v133
	v_mul_f32_e32 v28, v28, v120
	v_mul_f32_e32 v29, v29, v121
	v_mul_f32_e32 v24, v24, v124
	v_mul_f32_e32 v25, v25, v125
	v_mul_f32_e32 v20, v20, v128
	v_mul_f32_e32 v21, v21, v129
	v_mul_f32_e32 v30, v30, v122
	v_mul_f32_e32 v31, v31, v123
	v_mul_f32_e32 v26, v26, v126
	v_mul_f32_e32 v27, v27, v127
	v_mul_f32_e32 v22, v22, v130
	v_mul_f32_e32 v23, v23, v131
	v_mul_f32_e32 v18, v18, v134
	v_mul_f32_e32 v19, v19, v135
	v_mul_f32_e32 v16, v16, v132
	v_mul_f32_e32 v17, v17, v133
	v_mul_f32_e32 v60, v60, v120
	v_mul_f32_e32 v61, v61, v121
	v_mul_f32_e32 v56, v56, v124
	v_mul_f32_e32 v57, v57, v125
	v_mul_f32_e32 v52, v52, v128
	v_mul_f32_e32 v53, v53, v129
	v_mul_f32_e32 v62, v62, v122
	v_mul_f32_e32 v63, v63, v123
	v_mul_f32_e32 v58, v58, v126
	v_mul_f32_e32 v59, v59, v127
	v_mul_f32_e32 v54, v54, v130
	v_mul_f32_e32 v55, v55, v131
	v_mul_f32_e32 v50, v50, v134
	v_mul_f32_e32 v51, v51, v135
	v_mul_f32_e32 v48, v48, v132
	v_mul_f32_e32 v49, v49, v133
.LBB0_567:
	v_cndmask_b32_e64 v158, v136, v158, s[4:5]
	v_sub_f32_e32 v80, v80, v158
	v_sub_f32_e32 v81, v81, v158
	v_sub_f32_e32 v82, v82, v158
	v_sub_f32_e32 v83, v83, v158
	v_sub_f32_e32 v84, v84, v158
	v_sub_f32_e32 v85, v85, v158
	v_sub_f32_e32 v86, v86, v158
	v_sub_f32_e32 v87, v87, v158
	v_sub_f32_e32 v88, v88, v158
	v_sub_f32_e32 v89, v89, v158
	v_sub_f32_e32 v90, v90, v158
	v_sub_f32_e32 v91, v91, v158
	v_sub_f32_e32 v92, v92, v158
	v_sub_f32_e32 v93, v93, v158
	v_sub_f32_e32 v94, v94, v158
	v_sub_f32_e32 v95, v95, v158
	v_sub_f32_e32 v232, v76, v158
	v_sub_f32_e32 v235, v77, v158
	v_sub_f32_e32 v236, v78, v158
	v_exp_f32_e32 v133, v80
	v_exp_f32_e32 v135, v81
	v_exp_f32_e32 v131, v82
	v_exp_f32_e32 v134, v83
	v_exp_f32_e32 v130, v84
	v_exp_f32_e32 v132, v85
	v_exp_f32_e32 v128, v86
	v_exp_f32_e32 v129, v87
	v_exp_f32_e32 v125, v88
	v_exp_f32_e32 v127, v89
	v_exp_f32_e32 v124, v90
	v_exp_f32_e32 v126, v91
	v_exp_f32_e32 v121, v92
	v_exp_f32_e32 v123, v93
	v_exp_f32_e32 v120, v94
	v_exp_f32_e32 v122, v95
	v_sub_f32_e32 v178, v64, v158
	v_sub_f32_e32 v179, v65, v158
	v_sub_f32_e32 v213, v66, v158
	v_sub_f32_e32 v220, v67, v158
	v_sub_f32_e32 v221, v68, v158
	v_sub_f32_e32 v222, v69, v158
	v_sub_f32_e32 v223, v70, v158
	v_sub_f32_e32 v226, v71, v158
	v_sub_f32_e32 v227, v72, v158
	v_sub_f32_e32 v228, v73, v158
	v_sub_f32_e32 v229, v74, v158
	v_sub_f32_e32 v230, v75, v158
	v_sub_f32_e32 v237, v79, v158
	s_waitcnt lgkmcnt(0)
	s_barrier
	ds_read_b128 v[64:67], v187 offset:32768
	ds_read_b128 v[68:71], v187 offset:45056
	ds_read_b128 v[136:139], v189 offset:32768
	ds_read_b128 v[140:143], v189 offset:45056
	v_exp_f32_e32 v241, v236
	v_exp_f32_e32 v237, v237
	s_waitcnt lgkmcnt(3)
	v_mfma_f32_32x32x16_bf16 v[80:95], v[64:67], v[96:99], 0
	s_waitcnt lgkmcnt(2)
	v_mfma_f32_32x32x16_bf16 v[64:79], v[68:71], v[96:99], 0
	s_waitcnt lgkmcnt(1)
	v_mfma_f32_32x32x16_bf16 v[80:95], v[136:139], v[100:103], v[80:95]
	s_waitcnt lgkmcnt(0)
	v_mfma_f32_32x32x16_bf16 v[64:79], v[140:143], v[100:103], v[64:79]
	ds_read_b128 v[136:139], v190 offset:32768
	ds_read_b128 v[140:143], v190 offset:45056
	s_waitcnt lgkmcnt(1)
	v_mfma_f32_32x32x16_bf16 v[80:95], v[136:139], v[104:107], v[80:95]
	s_waitcnt lgkmcnt(0)
	v_mfma_f32_32x32x16_bf16 v[64:79], v[140:143], v[104:107], v[64:79]
	ds_read_b128 v[136:139], v191 offset:32768
	ds_read_b128 v[140:143], v191 offset:45056
	s_waitcnt lgkmcnt(1)
	v_mfma_f32_32x32x16_bf16 v[80:95], v[136:139], v[108:111], v[80:95]
	s_waitcnt lgkmcnt(0)
	v_mfma_f32_32x32x16_bf16 v[64:79], v[140:143], v[108:111], v[64:79]
	ds_read_b128 v[136:139], v192 offset:32768
	ds_read_b128 v[140:143], v192 offset:45056
	s_waitcnt lgkmcnt(1)
	v_mfma_f32_32x32x16_bf16 v[80:95], v[136:139], v[112:115], v[80:95]
	s_waitcnt lgkmcnt(0)
	v_mfma_f32_32x32x16_bf16 v[64:79], v[140:143], v[112:115], v[64:79]
	ds_read_b128 v[136:139], v193 offset:32768
	ds_read_b128 v[140:143], v193 offset:45056
	s_waitcnt lgkmcnt(1)
	v_mfma_f32_32x32x16_bf16 v[80:95], v[136:139], v[116:119], v[80:95]
	s_waitcnt lgkmcnt(0)
	v_mfma_f32_32x32x16_bf16 v[64:79], v[140:143], v[116:119], v[64:79]
	ds_read_b128 v[136:139], v194 offset:32768
	ds_read_b128 v[140:143], v194 offset:45056
	ds_read_b128 v[144:147], v171
	s_waitcnt lgkmcnt(0)
	v_mfma_f32_32x32x16_bf16 v[80:95], v[136:139], v[144:147], v[80:95]
	v_mfma_f32_32x32x16_bf16 v[64:79], v[140:143], v[144:147], v[64:79]
	ds_read_b128 v[136:139], v195 offset:32768
	ds_read_b128 v[140:143], v195 offset:45056
	ds_read_b128 v[144:147], v171 offset:1024
	s_waitcnt lgkmcnt(0)
	v_mfma_f32_32x32x16_bf16 v[80:95], v[136:139], v[144:147], v[80:95]
	v_mfma_f32_32x32x16_bf16 v[64:79], v[140:143], v[144:147], v[64:79]
	ds_read_b128 v[136:139], v196 offset:32768
	ds_read_b128 v[140:143], v196 offset:45056
	ds_read_b128 v[144:147], v171 offset:2048
	s_waitcnt lgkmcnt(0)
	v_mfma_f32_32x32x16_bf16 v[80:95], v[136:139], v[144:147], v[80:95]
	v_mfma_f32_32x32x16_bf16 v[64:79], v[140:143], v[144:147], v[64:79]
	ds_read_b128 v[136:139], v197 offset:32768
	ds_read_b128 v[140:143], v197 offset:45056
	ds_read_b128 v[144:147], v171 offset:3072
	s_waitcnt lgkmcnt(0)
	v_mfma_f32_32x32x16_bf16 v[80:95], v[136:139], v[144:147], v[80:95]
	v_mfma_f32_32x32x16_bf16 v[64:79], v[140:143], v[144:147], v[64:79]
	ds_read_b128 v[136:139], v199 offset:32768
	ds_read_b128 v[140:143], v199 offset:45056
	ds_read_b128 v[144:147], v171 offset:4096
	s_waitcnt lgkmcnt(0)
	v_mfma_f32_32x32x16_bf16 v[80:95], v[136:139], v[144:147], v[80:95]
	v_mfma_f32_32x32x16_bf16 v[64:79], v[140:143], v[144:147], v[64:79]
	ds_read_b128 v[136:139], v198 offset:32768
	ds_read_b128 v[140:143], v198 offset:45056
	ds_read_b128 v[144:147], v171 offset:5120
	s_waitcnt lgkmcnt(0)
	v_mfma_f32_32x32x16_bf16 v[80:95], v[136:139], v[144:147], v[80:95]
	v_add_f32_e32 v136, 0, v133
	v_add_f32_e32 v136, v135, v136
	v_add_f32_e32 v136, v131, v136
	v_add_f32_e32 v136, v134, v136
	v_add_f32_e32 v136, v130, v136
	v_add_f32_e32 v136, v132, v136
	v_add_f32_e32 v136, v128, v136
	v_add_f32_e32 v136, v129, v136
	v_add_f32_e32 v136, v125, v136
	v_add_f32_e32 v136, v127, v136
	v_add_f32_e32 v136, v124, v136
	v_add_f32_e32 v136, v126, v136
	v_mfma_f32_32x32x16_bf16 v[64:79], v[140:143], v[144:147], v[64:79]
	v_exp_f32_e32 v140, v178
	v_add_f32_e32 v136, v121, v136
	v_exp_f32_e32 v141, v179
	v_add_f32_e32 v136, v123, v136
	v_exp_f32_e32 v142, v213
	v_add_f32_e32 v136, v120, v136
	v_exp_f32_e32 v143, v220
	v_add_f32_e32 v136, v122, v136
	v_exp_f32_e32 v178, v221
	v_add_f32_e32 v136, v140, v136
	v_exp_f32_e32 v179, v222
	v_add_f32_e32 v136, v141, v136
	v_exp_f32_e32 v213, v223
	v_add_f32_e32 v136, v142, v136
	v_exp_f32_e32 v223, v226
	v_add_f32_e32 v136, v143, v136
	v_exp_f32_e32 v226, v227
	v_add_f32_e32 v136, v178, v136
	v_exp_f32_e32 v227, v228
	v_add_f32_e32 v136, v179, v136
	v_exp_f32_e32 v228, v229
	v_add_f32_e32 v136, v213, v136
	v_exp_f32_e32 v229, v230
	v_add_f32_e32 v136, v223, v136
	v_exp_f32_e32 v230, v232
	v_add_f32_e32 v136, v226, v136
	v_exp_f32_e32 v232, v235
	v_add_f32_e32 v136, v227, v136
	v_add_f32_e32 v136, v228, v136
	v_add_f32_e32 v136, v229, v136
	v_add_f32_e32 v136, v230, v136
	v_add_f32_e32 v136, v232, v136
	v_add_f32_e32 v136, v241, v136
	v_add_f32_e32 v235, v237, v136
	v_mov_b32_e32 v236, v235
	v_cvt_pk_bf16_f32 v136, v133, v135
	v_cvt_pk_bf16_f32 v137, v131, v134
	v_cvt_pk_bf16_f32 v138, v130, v132
	s_nop 1
	v_permlane32_swap_b32_e32 v235, v236
	v_cvt_pk_bf16_f32 v139, v128, v129
	v_permlane32_swap_b32_e32 v136, v138
	v_cvt_pk_bf16_f32 v144, v125, v127
	v_cvt_pk_bf16_f32 v145, v124, v126
	v_cvt_pk_bf16_f32 v146, v121, v123
	v_cvt_pk_bf16_f32 v147, v120, v122
	v_cvt_pk_bf16_f32 v220, v140, v141
	v_cvt_pk_bf16_f32 v221, v142, v143
	v_cvt_pk_bf16_f32 v222, v178, v179
	v_cvt_pk_bf16_f32 v223, v213, v223
	v_cvt_pk_bf16_f32 v238, v226, v227
	v_cvt_pk_bf16_f32 v239, v228, v229
	v_cvt_pk_bf16_f32 v240, v230, v232
	v_cvt_pk_bf16_f32 v241, v241, v237
	v_permlane32_swap_b32_e32 v137, v139
	v_permlane32_swap_b32_e32 v144, v146
	v_permlane32_swap_b32_e32 v145, v147
	v_permlane32_swap_b32_e32 v220, v222
	v_permlane32_swap_b32_e32 v221, v223
	v_permlane32_swap_b32_e32 v238, v240
	v_permlane32_swap_b32_e32 v239, v241
	s_add_i32 s4, s15, 64
	s_cmp_lt_u32 s16, 2
	s_cselect_b32 s4, s4, s14
	s_ashr_i32 s5, s4, 31
	s_lshl_b64 s[76:77], s[4:5], 11
	s_mul_hi_i32 s79, s4, s87
	s_mul_i32 s78, s4, s87
	v_lshl_add_u64 v[120:121], v[148:149], 0, s[76:77]
	v_lshl_add_u64 v[124:125], v[156:157], 0, s[76:77]
	v_lshl_add_u64 v[130:131], v[150:151], 0, s[78:79]
	v_lshl_add_u64 v[134:135], v[152:153], 0, s[78:79]
	v_lshl_add_u64 v[140:141], v[154:155], 0, s[78:79]
	global_load_dwordx4 v[120:123], v[120:121], off
	s_nop 0
	global_load_dwordx4 v[124:127], v[124:125], off
	s_nop 0
	global_load_dwordx4 v[128:131], v[130:131], off
	s_nop 0
	global_load_dwordx4 v[132:135], v[134:135], off
	s_nop 0
	global_load_dwordx4 v[140:143], v[140:141], off
	ds_read_b64_tr_b16 v[242:243], v175 offset:0
	ds_read_b64_tr_b16 v[244:245], v175 offset:0x800
	ds_read_b64_tr_b16 v[246:247], v175 offset:0x1000
	ds_read_b64_tr_b16 v[248:249], v175 offset:0x1800
	ds_read_b64_tr_b16 v[250:251], v175 offset:0x2000
	ds_read_b64_tr_b16 v[252:253], v175 offset:0x2800
	ds_read_b64_tr_b16 v[226:227], v175 offset:0x3000
	ds_read_b64_tr_b16 v[228:229], v175 offset:0x3800
	s_waitcnt lgkmcnt(0)
	s_nop 0
	v_mfma_f32_32x32x16_bf16 v[0:15], v[136:139], v[242:245], v[0:15]
	v_mfma_f32_32x32x16_bf16 v[0:15], v[144:147], v[246:249], v[0:15]
	v_mfma_f32_32x32x16_bf16 v[0:15], v[220:223], v[250:253], v[0:15]
	v_mfma_f32_32x32x16_bf16 v[0:15], v[238:241], v[226:229], v[0:15]
	ds_read_b64_tr_b16 v[226:227], v175 offset:0x200
	ds_read_b64_tr_b16 v[228:229], v175 offset:0xa00
	ds_read_b64_tr_b16 v[242:243], v175 offset:0x1200
	ds_read_b64_tr_b16 v[244:245], v175 offset:0x1a00
	ds_read_b64_tr_b16 v[246:247], v175 offset:0x2200
	ds_read_b64_tr_b16 v[248:249], v175 offset:0x2a00
	ds_read_b64_tr_b16 v[250:251], v175 offset:0x3200
	ds_read_b64_tr_b16 v[252:253], v175 offset:0x3a00
	s_waitcnt lgkmcnt(0)
	s_nop 0
	v_mfma_f32_32x32x16_bf16 v[32:47], v[136:139], v[226:229], v[32:47]
	ds_read_b64_tr_b16 v[226:227], v175 offset:0x400
	ds_read_b64_tr_b16 v[228:229], v175 offset:0xc00
	v_mfma_f32_32x32x16_bf16 v[32:47], v[144:147], v[242:245], v[32:47]
	ds_read_b64_tr_b16 v[242:243], v175 offset:0x1400
	ds_read_b64_tr_b16 v[244:245], v175 offset:0x1c00
	v_mfma_f32_32x32x16_bf16 v[32:47], v[220:223], v[246:249], v[32:47]
	ds_read_b64_tr_b16 v[246:247], v175 offset:0x2400
	ds_read_b64_tr_b16 v[248:249], v175 offset:0x2c00
	v_mfma_f32_32x32x16_bf16 v[32:47], v[238:241], v[250:253], v[32:47]
	ds_read_b64_tr_b16 v[250:251], v175 offset:0x3400
	ds_read_b64_tr_b16 v[252:253], v175 offset:0x3c00
	s_waitcnt lgkmcnt(0)
	v_mfma_f32_32x32x16_bf16 v[16:31], v[136:139], v[226:229], v[16:31]
	ds_read_b64_tr_b16 v[226:227], v175 offset:0x600
	ds_read_b64_tr_b16 v[228:229], v175 offset:0xe00
	v_mfma_f32_32x32x16_bf16 v[16:31], v[144:147], v[242:245], v[16:31]
	ds_read_b64_tr_b16 v[242:243], v175 offset:0x1600
	ds_read_b64_tr_b16 v[244:245], v175 offset:0x1e00
	v_mfma_f32_32x32x16_bf16 v[16:31], v[220:223], v[246:249], v[16:31]
	ds_read_b64_tr_b16 v[246:247], v175 offset:0x2600
	ds_read_b64_tr_b16 v[248:249], v175 offset:0x2e00
	v_mfma_f32_32x32x16_bf16 v[16:31], v[238:241], v[250:253], v[16:31]
	ds_read_b64_tr_b16 v[250:251], v175 offset:0x3600
	ds_read_b64_tr_b16 v[252:253], v175 offset:0x3e00
	s_waitcnt lgkmcnt(0)
	v_mfma_f32_32x32x16_bf16 v[48:63], v[136:139], v[226:229], v[48:63]
	v_max_f32_e32 v136, v81, v81
	v_max_f32_e32 v137, v80, v80
	v_max_f32_e32 v136, v137, v136
	v_max3_f32 v136, v136, v82, v83
	v_max3_f32 v136, v136, v84, v85
	v_max3_f32 v136, v136, v86, v87
	v_max3_f32 v136, v136, v88, v89
	v_max3_f32 v136, v136, v90, v91
	v_mfma_f32_32x32x16_bf16 v[48:63], v[144:147], v[242:245], v[48:63]
	v_max3_f32 v136, v136, v92, v93
	v_max3_f32 v136, v136, v94, v95
	v_max3_f32 v136, v136, v64, v65
	v_max3_f32 v136, v136, v66, v67
	v_max3_f32 v136, v136, v68, v69
	v_max3_f32 v136, v136, v70, v71
	v_max3_f32 v136, v136, v72, v73
	v_max3_f32 v136, v136, v74, v75
	v_mfma_f32_32x32x16_bf16 v[48:63], v[220:223], v[246:249], v[48:63]
	v_max3_f32 v136, v136, v76, v77
	v_max3_f32 v136, v136, v78, v79
	v_mov_b32_e32 v137, v136
	s_nop 1
	v_permlane32_swap_b32_e32 v136, v137
	v_max_f32_e32 v137, v137, v137
	v_max_f32_e32 v136, v136, v136
	v_max_f32_e32 v136, v136, v137
	v_sub_f32_e32 v137, v136, v158
	v_cmp_ge_f32_e32 vcc, s90, v137
	v_max_f32_e32 v137, v158, v158
	v_mfma_f32_32x32x16_bf16 v[48:63], v[238:241], v[250:253], v[48:63]
	v_max_f32_e32 v136, v137, v136
	v_sub_f32_e32 v137, v158, v136
	v_exp_f32_e32 v137, v137
	s_cmp_eq_u64 vcc, exec
	s_cselect_b64 s[4:5], -1, 0
	s_barrier
	s_waitcnt vmcnt(0)
	v_cndmask_b32_e64 v232, v137, 1.0, s[4:5]
	v_cmp_gt_f32_e32 vcc, 1.0, v232
	s_waitcnt vmcnt(4)
	ds_write_b128 v182, v[120:123] offset:16384
	s_waitcnt vmcnt(3)
	ds_write_b128 v183, v[124:127] offset:16384
	s_waitcnt vmcnt(2)
	ds_write_b128 v184, v[128:131] offset:57344
	s_waitcnt vmcnt(1)
	ds_write_b128 v185, v[132:135] offset:57344
	s_waitcnt vmcnt(0)
	ds_write_b128 v186, v[140:143] offset:57344
	s_cbranch_vccz .LBB0_571
	s_and_saveexec_b64 s[6:7], s[2:3]
	ds_write_b32 v173, v232 offset:128
	s_or_b64 exec, exec, s[6:7]
	s_waitcnt lgkmcnt(0)
	v_add_u32_e32 v132, v169, v176
	ds_read_b128 v[120:123], v132 offset:224
	ds_read_b128 v[124:127], v132 offset:192
	ds_read_b128 v[128:131], v132 offset:160
	ds_read_b128 v[132:135], v132 offset:128
	s_waitcnt lgkmcnt(3)
	v_mul_f32_e32 v12, v12, v120
	v_mul_f32_e32 v13, v13, v121
	s_waitcnt lgkmcnt(2)
	v_mul_f32_e32 v8, v8, v124
	v_mul_f32_e32 v9, v9, v125
	s_waitcnt lgkmcnt(1)
	v_mul_f32_e32 v4, v4, v128
	v_mul_f32_e32 v5, v5, v129
	v_mul_f32_e32 v14, v14, v122
	v_mul_f32_e32 v15, v15, v123
	v_mul_f32_e32 v10, v10, v126
	v_mul_f32_e32 v11, v11, v127
	v_mul_f32_e32 v6, v6, v130
	v_mul_f32_e32 v7, v7, v131
	s_waitcnt lgkmcnt(0)
	v_mul_f32_e32 v2, v2, v134
	v_mul_f32_e32 v3, v3, v135
	v_mul_f32_e32 v0, v0, v132
	v_mul_f32_e32 v1, v1, v133
	v_mul_f32_e32 v44, v44, v120
	v_mul_f32_e32 v45, v45, v121
	v_mul_f32_e32 v40, v40, v124
	v_mul_f32_e32 v41, v41, v125
	v_mul_f32_e32 v36, v36, v128
	v_mul_f32_e32 v37, v37, v129
	v_mul_f32_e32 v46, v46, v122
	v_mul_f32_e32 v47, v47, v123
	v_mul_f32_e32 v42, v42, v126
	v_mul_f32_e32 v43, v43, v127
	v_mul_f32_e32 v38, v38, v130
	v_mul_f32_e32 v39, v39, v131
	v_mul_f32_e32 v34, v34, v134
	v_mul_f32_e32 v35, v35, v135
	v_mul_f32_e32 v32, v32, v132
	v_mul_f32_e32 v33, v33, v133
	v_mul_f32_e32 v28, v28, v120
	v_mul_f32_e32 v29, v29, v121
	v_mul_f32_e32 v24, v24, v124
	v_mul_f32_e32 v25, v25, v125
	v_mul_f32_e32 v20, v20, v128
	v_mul_f32_e32 v21, v21, v129
	v_mul_f32_e32 v30, v30, v122
	v_mul_f32_e32 v31, v31, v123
	v_mul_f32_e32 v26, v26, v126
	v_mul_f32_e32 v27, v27, v127
	v_mul_f32_e32 v22, v22, v130
	v_mul_f32_e32 v23, v23, v131
	v_mul_f32_e32 v18, v18, v134
	v_mul_f32_e32 v19, v19, v135
	v_mul_f32_e32 v16, v16, v132
	v_mul_f32_e32 v17, v17, v133
	v_mul_f32_e32 v60, v60, v120
	v_mul_f32_e32 v61, v61, v121
	v_mul_f32_e32 v56, v56, v124
	v_mul_f32_e32 v57, v57, v125
	v_mul_f32_e32 v52, v52, v128
	v_mul_f32_e32 v53, v53, v129
	v_mul_f32_e32 v62, v62, v122
	v_mul_f32_e32 v63, v63, v123
	v_mul_f32_e32 v58, v58, v126
	v_mul_f32_e32 v59, v59, v127
	v_mul_f32_e32 v54, v54, v130
	v_mul_f32_e32 v55, v55, v131
	v_mul_f32_e32 v50, v50, v134
	v_mul_f32_e32 v51, v51, v135
	v_mul_f32_e32 v48, v48, v132
	v_mul_f32_e32 v49, v49, v133
.LBB0_571:
	v_cndmask_b32_e64 v158, v136, v158, s[4:5]
	v_sub_f32_e32 v80, v80, v158
	v_sub_f32_e32 v81, v81, v158
	v_sub_f32_e32 v82, v82, v158
	v_sub_f32_e32 v83, v83, v158
	v_sub_f32_e32 v84, v84, v158
	v_sub_f32_e32 v85, v85, v158
	v_sub_f32_e32 v86, v86, v158
	v_sub_f32_e32 v87, v87, v158
	v_sub_f32_e32 v88, v88, v158
	v_sub_f32_e32 v89, v89, v158
	v_sub_f32_e32 v90, v90, v158
	v_sub_f32_e32 v91, v91, v158
	v_sub_f32_e32 v92, v92, v158
	v_sub_f32_e32 v93, v93, v158
	v_sub_f32_e32 v94, v94, v158
	v_sub_f32_e32 v95, v95, v158
	v_exp_f32_e32 v136, v80
	v_exp_f32_e32 v230, v81
	v_exp_f32_e32 v137, v82
	v_exp_f32_e32 v229, v83
	v_exp_f32_e32 v138, v84
	v_exp_f32_e32 v228, v85
	v_exp_f32_e32 v139, v86
	v_exp_f32_e32 v213, v87
	v_exp_f32_e32 v144, v88
	v_exp_f32_e32 v147, v89
	v_exp_f32_e32 v145, v90
	v_exp_f32_e32 v146, v91
	v_exp_f32_e32 v141, v92
	v_exp_f32_e32 v143, v93
	v_exp_f32_e32 v140, v94
	v_exp_f32_e32 v142, v95
	v_add_f32_e32 v80, v231, v233
	v_fmac_f32_e32 v80, v200, v188
	v_add_f32_e32 v188, v235, v236
	s_addk_i32 s15, 0x80
	s_add_i32 s13, s13, 2
	s_addk_i32 s14, 0x80
	v_fmac_f32_e32 v188, v80, v234
	v_sub_f32_e32 v132, v64, v158
	v_sub_f32_e32 v133, v65, v158
	v_sub_f32_e32 v134, v66, v158
	v_sub_f32_e32 v135, v67, v158
	v_sub_f32_e32 v124, v68, v158
	v_sub_f32_e32 v125, v69, v158
	v_sub_f32_e32 v126, v70, v158
	v_sub_f32_e32 v127, v71, v158
	v_sub_f32_e32 v128, v72, v158
	v_sub_f32_e32 v129, v73, v158
	v_sub_f32_e32 v130, v74, v158
	v_sub_f32_e32 v131, v75, v158
	v_sub_f32_e32 v120, v76, v158
	v_sub_f32_e32 v121, v77, v158
	v_sub_f32_e32 v122, v78, v158
	v_sub_f32_e32 v123, v79, v158
	s_cmp_ge_u32 s13, s12
	s_waitcnt lgkmcnt(0)
	s_barrier
	s_cbranch_scc1 .LBB0_573
	v_mov_b32_e32 v200, v232
	s_branch .LBB0_563
